# lever 7 instruction selection: attention row max as 16-op v_max3 tree (no canonicalising copies) + cross-half max via v_permlane32_swap instead of ds_bpermute+lgkmcnt(0), on top of v5
# baseline (speedup 1.0000x reference)
; template <int DQK, bool HAS_LSE>
; __device__ __forceinline__ void unit(LAS unsigned char* lds, const Desc& d) {
;     ...
;             float mx = fmaxf(p0[0], p1[0]);
; #pragma unroll
;             for (int i = 1; i < 16; ++i) mx = fmaxf(mx, fmaxf(p0[i], p1[i]));
;             mx = fmaxf(mx, __shfl_xor(mx, 32));
;             const float mn = fmaxf(m, mx), corr = __builtin_amdgcn_exp2f(m - mn); const bool grew = __any(mn > m); m = mn;
;             float ls = 0.f;
; #pragma unroll
;             for (int i = 0; i < 16; ++i) { p0[i] = __builtin_amdgcn_exp2f(p0[i] - mn); p1[i] = __builtin_amdgcn_exp2f(p1[i] - mn); ls += p0[i] + p1[i]; }
;             l = l * corr + ls;
;             if (grew) {
; #pragma unroll
;                 for (int db = 0; db < 4; ++db)
; #pragma unroll
;                     for (int i = 0; i < 16; ++i) o[db][i] *= corr;
;             }
.LBB0_520:
	s_nop 3
	v_max3_f32 v153, v68, v69, v70
	v_max3_f32 v154, v71, v72, v73
	v_max3_f32 v178, v74, v75, v76
	v_max3_f32 v179, v77, v78, v79
	v_max3_f32 v153, v153, v80, v81
	v_max3_f32 v154, v154, v82, v83
	v_max3_f32 v178, v178, v84, v85
	v_max3_f32 v179, v179, v86, v87
	v_max3_f32 v153, v153, v88, v89
	v_max3_f32 v154, v154, v90, v91
	v_max3_f32 v178, v178, v92, v93
	v_max3_f32 v179, v179, v94, v95
	v_max3_f32 v153, v153, v96, v97
	v_max3_f32 v154, v154, v98, v99
	v_max3_f32 v153, v153, v178, v179
	v_max_f32_e32 v153, v153, v154
	v_mov_b32_e32 v154, v153
	s_nop 1
	v_permlane32_swap_b32_e32 v154, v153
	v_max3_f32 v153, v67, v153, v154
	v_sub_f32_e32 v154, v67, v153
	v_exp_f32_e32 v154, v154
	v_cmp_gt_f32_e32 vcc, v153, v67
	s_cbranch_vccz .LBB0_522
	v_mul_f32_e32 v64, v64, v154
	v_mul_f32_e32 v65, v65, v154
	v_mul_f32_e32 v62, v62, v154
	v_mul_f32_e32 v63, v63, v154
	v_mul_f32_e32 v60, v60, v154
	v_mul_f32_e32 v61, v61, v154
	v_mul_f32_e32 v58, v58, v154
	v_mul_f32_e32 v59, v59, v154
	v_mul_f32_e32 v56, v56, v154
	v_mul_f32_e32 v57, v57, v154
	v_mul_f32_e32 v54, v54, v154
	v_mul_f32_e32 v55, v55, v154
	v_mul_f32_e32 v52, v52, v154
	v_mul_f32_e32 v53, v53, v154
	v_mul_f32_e32 v50, v50, v154
	v_mul_f32_e32 v51, v51, v154
	v_mul_f32_e32 v48, v48, v154
	v_mul_f32_e32 v49, v49, v154
	v_mul_f32_e32 v46, v46, v154
	v_mul_f32_e32 v47, v47, v154
	v_mul_f32_e32 v44, v44, v154
	v_mul_f32_e32 v45, v45, v154
	v_mul_f32_e32 v42, v42, v154
	v_mul_f32_e32 v43, v43, v154
	v_mul_f32_e32 v40, v40, v154
	v_mul_f32_e32 v41, v41, v154
	v_mul_f32_e32 v38, v38, v154
	v_mul_f32_e32 v39, v39, v154
	v_mul_f32_e32 v36, v36, v154
	v_mul_f32_e32 v37, v37, v154
	v_mul_f32_e32 v34, v34, v154
	v_mul_f32_e32 v35, v35, v154
	v_mul_f32_e32 v32, v32, v154
	v_mul_f32_e32 v33, v33, v154
	v_mul_f32_e32 v30, v30, v154
	v_mul_f32_e32 v31, v31, v154
	v_mul_f32_e32 v28, v28, v154
	v_mul_f32_e32 v29, v29, v154
	v_mul_f32_e32 v26, v26, v154
	v_mul_f32_e32 v27, v27, v154
	v_mul_f32_e32 v24, v24, v154
	v_mul_f32_e32 v25, v25, v154
	v_mul_f32_e32 v22, v22, v154
	v_mul_f32_e32 v23, v23, v154
	v_mul_f32_e32 v20, v20, v154
	v_mul_f32_e32 v21, v21, v154
	v_mul_f32_e32 v18, v18, v154
	v_mul_f32_e32 v19, v19, v154
	v_mul_f32_e32 v16, v16, v154
	v_mul_f32_e32 v17, v17, v154
	v_mul_f32_e32 v14, v14, v154
	v_mul_f32_e32 v15, v15, v154
	v_mul_f32_e32 v12, v12, v154
	v_mul_f32_e32 v13, v13, v154
	v_mul_f32_e32 v10, v10, v154
	v_mul_f32_e32 v11, v11, v154
	v_mul_f32_e32 v8, v8, v154
	v_mul_f32_e32 v9, v9, v154
	v_mul_f32_e32 v6, v6, v154
	v_mul_f32_e32 v7, v7, v154
	v_mul_f32_e32 v4, v4, v154
	v_mul_f32_e32 v5, v5, v154
	v_mul_f32_e32 v2, v2, v154
	v_mul_f32_e32 v3, v3, v154

; template <int DQK, bool HAS_LSE>
; __device__ __forceinline__ void unit(LAS unsigned char* lds, const Desc& d) {
;     ...
;             float mx = fmaxf(p0[0], p1[0]);
; #pragma unroll
;             for (int i = 1; i < 16; ++i) mx = fmaxf(mx, fmaxf(p0[i], p1[i]));
;             mx = fmaxf(mx, __shfl_xor(mx, 32));
;             const float mn = fmaxf(m, mx), corr = __builtin_amdgcn_exp2f(m - mn); const bool grew = __any(mn > m); m = mn;
;             float ls = 0.f;
; #pragma unroll
;             for (int i = 0; i < 16; ++i) { p0[i] = __builtin_amdgcn_exp2f(p0[i] - mn); p1[i] = __builtin_amdgcn_exp2f(p1[i] - mn); ls += p0[i] + p1[i]; }
;             l = l * corr + ls;
;             if (grew) {
; #pragma unroll
;                 for (int db = 0; db < 4; ++db)
; #pragma unroll
;                     for (int i = 0; i < 16; ++i) o[db][i] *= corr;
;             }
.LBB0_1997:
	s_nop 4
	v_max3_f32 v0, v66, v67, v68
	v_max3_f32 v186, v69, v70, v71
	v_max3_f32 v189, v72, v73, v74
	v_max3_f32 v190, v75, v76, v77
	v_max3_f32 v0, v0, v78, v79
	v_max3_f32 v186, v186, v80, v81
	v_max3_f32 v189, v189, v82, v83
	v_max3_f32 v190, v190, v84, v85
	v_max3_f32 v0, v0, v86, v87
	v_max3_f32 v186, v186, v88, v89
	v_max3_f32 v189, v189, v90, v91
	v_max3_f32 v190, v190, v92, v93
	v_max3_f32 v0, v0, v94, v95
	v_max3_f32 v186, v186, v96, v97
	v_max3_f32 v0, v0, v189, v190
	v_max_f32_e32 v0, v0, v186
	v_mov_b32_e32 v186, v0
	s_nop 1
	v_permlane32_swap_b32_e32 v186, v0
	v_max3_f32 v186, v188, v0, v186
	v_sub_f32_e32 v0, v188, v186
	v_exp_f32_e32 v0, v0
	v_cmp_gt_f32_e32 vcc, v186, v188
	s_cbranch_vccz .LBB0_1999
	v_mul_f32_e32 v64, v64, v0
	v_mul_f32_e32 v65, v65, v0
	v_mul_f32_e32 v62, v62, v0
	v_mul_f32_e32 v63, v63, v0
	v_mul_f32_e32 v60, v60, v0
	v_mul_f32_e32 v61, v61, v0
	v_mul_f32_e32 v58, v58, v0
	v_mul_f32_e32 v59, v59, v0
	v_mul_f32_e32 v56, v56, v0
	v_mul_f32_e32 v57, v57, v0
	v_mul_f32_e32 v54, v54, v0
	v_mul_f32_e32 v55, v55, v0
	v_mul_f32_e32 v52, v52, v0
	v_mul_f32_e32 v53, v53, v0
	v_mul_f32_e32 v50, v50, v0
	v_mul_f32_e32 v51, v51, v0
	v_mul_f32_e32 v48, v48, v0
	v_mul_f32_e32 v49, v49, v0
	v_mul_f32_e32 v46, v46, v0
	v_mul_f32_e32 v47, v47, v0
	v_mul_f32_e32 v44, v44, v0
	v_mul_f32_e32 v45, v45, v0
	v_mul_f32_e32 v42, v42, v0
	v_mul_f32_e32 v43, v43, v0
	v_mul_f32_e32 v40, v40, v0
	v_mul_f32_e32 v41, v41, v0
	v_mul_f32_e32 v38, v38, v0
	v_mul_f32_e32 v39, v39, v0
	v_mul_f32_e32 v36, v36, v0
	v_mul_f32_e32 v37, v37, v0
	v_mul_f32_e32 v34, v34, v0
	v_mul_f32_e32 v35, v35, v0
	v_mul_f32_e32 v32, v32, v0
	v_mul_f32_e32 v33, v33, v0
	v_mul_f32_e32 v30, v30, v0
	v_mul_f32_e32 v31, v31, v0
	v_mul_f32_e32 v28, v28, v0
	v_mul_f32_e32 v29, v29, v0
	v_mul_f32_e32 v26, v26, v0
	v_mul_f32_e32 v27, v27, v0
	v_mul_f32_e32 v24, v24, v0
	v_mul_f32_e32 v25, v25, v0
	v_mul_f32_e32 v22, v22, v0
	v_mul_f32_e32 v23, v23, v0
	v_mul_f32_e32 v20, v20, v0
	v_mul_f32_e32 v21, v21, v0
	v_mul_f32_e32 v18, v18, v0
	v_mul_f32_e32 v19, v19, v0
	v_mul_f32_e32 v16, v16, v0
	v_mul_f32_e32 v17, v17, v0
	v_mul_f32_e32 v14, v14, v0
	v_mul_f32_e32 v15, v15, v0
	v_mul_f32_e32 v12, v12, v0
	v_mul_f32_e32 v13, v13, v0
	v_mul_f32_e32 v10, v10, v0
	v_mul_f32_e32 v11, v11, v0
	v_mul_f32_e32 v8, v8, v0
	v_mul_f32_e32 v9, v9, v0
	v_mul_f32_e32 v6, v6, v0
	v_mul_f32_e32 v7, v7, v0
	v_mul_f32_e32 v4, v4, v0
	v_mul_f32_e32 v5, v5, v0
	v_mul_f32_e32 v2, v2, v0
	v_mul_f32_e32 v3, v3, v0
